# LayerNorm phases: non-temporal hint (nt) on the read-once row loads of the 8 LayerNorm loops
# speedup vs baseline: 1.0008x; 1.0008x over previous
.LBB0_937:
	s_mov_b32 s4, 0x3e0f83e1
	v_mul_hi_i32 v0, v41, s4
	v_lshrrev_b32_e32 v1, 31, v0
	v_ashrrev_i32_e32 v0, 11, v0
	v_add_u32_e32 v42, v0, v1
	s_movk_i32 s4, 0xdf00
	v_mad_i32_i24 v1, v42, s4, v41
	s_movk_i32 s4, 0x100
	v_cmp_gt_i32_e64 s[12:13], s4, v1
	s_movk_i32 s4, 0xff
	v_cmp_lt_i32_e32 vcc, s4, v1
	s_and_saveexec_b64 s[4:5], vcc
	s_xor_b64 s[4:5], exec, s[4:5]
	v_mul_i32_i24_e32 v0, 0xffffdf00, v42
	v_lshl_add_u32 v0, v42, 13, v0
	v_add3_u32 v0, v41, v0, s2
	s_or_saveexec_b64 s[4:5], s[4:5]
	v_mov_b64_e32 v[2:3], s[88:89]
	s_xor_b64 exec, exec, s[4:5]
	v_lshl_add_u32 v0, v42, 8, v1
	v_mov_b64_e32 v[2:3], s[70:71]
	s_or_b64 exec, exec, s[4:5]
	v_ashrrev_i32_e32 v1, 31, v0
	v_lshlrev_b64 v[0:1], 12, v[0:1]
	v_lshl_add_u64 v[0:1], v[2:3], 0, v[0:1]
	v_lshl_add_u64 v[0:1], v[0:1], 0, v[24:25]
	global_load_dwordx4 v[12:15], v[0:1], off nt
	global_load_dwordx4 v[8:11], v[0:1], off offset:1024 nt
	global_load_dwordx4 v[4:7], v[0:1], off offset:2048 nt
	s_nop 0
	global_load_dwordx4 v[0:3], v[0:1], off offset:3072 nt
	s_waitcnt vmcnt(3)
	v_mov_b32_e32 v32, v13
	v_mov_b32_e32 v33, v14
	v_mov_b32_e32 v44, v12
	v_mov_b32_e32 v45, v15
	s_waitcnt vmcnt(2)
	v_mov_b32_e32 v46, v9
	v_mov_b32_e32 v47, v10
	v_mov_b32_e32 v48, v8
	v_mov_b32_e32 v49, v11
	v_pk_add_f32 v[32:33], v[32:33], v[44:45]
	v_pk_add_f32 v[44:45], v[46:47], v[48:49]
	v_add_f32_e32 v43, v32, v33
	v_pk_add_f32 v[32:33], v[44:45], v[44:45] op_sel:[0,1] op_sel_hi:[1,0]
	s_waitcnt vmcnt(1)
	v_add_f32_e32 v50, v4, v5
	v_add_f32_e32 v52, v6, v7
	s_waitcnt vmcnt(0)
	v_mov_b32_e32 v55, v0
	v_mov_b32_e32 v51, v2
	v_mov_b32_e32 v53, v3
	v_add_f32_e32 v54, 0, v43
	v_mov_b32_e32 v33, v1
	v_pk_add_f32 v[46:47], v[50:51], v[52:53]
	v_pk_add_f32 v[32:33], v[54:55], v[32:33]
	s_nop 0
	v_pk_add_f32 v[32:33], v[32:33], v[46:47]
	s_nop 0
	v_add_f32_e32 v32, v32, v33
	s_nop 1
	v_add_f32_dpp v32, v32, v32 quad_perm:[1,0,3,2] row_mask:0xf bank_mask:0xf
	s_nop 1
	v_add_f32_dpp v32, v32, v32 quad_perm:[2,3,0,1] row_mask:0xf bank_mask:0xf
	s_nop 1
	v_add_f32_dpp v32, v32, v32 row_half_mirror row_mask:0xf bank_mask:0xf
	s_nop 1
	v_add_f32_dpp v32, v32, v32 row_mirror row_mask:0xf bank_mask:0xf
	v_mov_b32_e32 v33, v32
	s_nop 1
	v_permlane16_swap_b32 v32, v33
	v_add_f32_e32 v32, v32, v33
	v_mov_b32_e32 v33, v32
	s_nop 1
	v_permlane32_swap_b32 v32, v33
	v_add_f32_e32 v43, v32, v33
	v_fmamk_f32 v33, v43, 0xba800000, v15
	v_fmamk_f32 v32, v43, 0xba800000, v14
	v_fmamk_f32 v13, v43, 0xba800000, v13
	v_fmac_f32_e32 v12, 0xba800000, v43
	v_fmamk_f32 v11, v43, 0xba800000, v11
	v_fmamk_f32 v10, v43, 0xba800000, v10
	v_fmamk_f32 v9, v43, 0xba800000, v9
	v_fmac_f32_e32 v8, 0xba800000, v43
	v_pk_mul_f32 v[14:15], v[32:33], v[32:33]
	v_pk_mul_f32 v[44:45], v[12:13], v[12:13]
	v_pk_mul_f32 v[46:47], v[10:11], v[10:11]
	v_pk_mul_f32 v[48:49], v[8:9], v[8:9]
	v_fmamk_f32 v6, v43, 0xba800000, v6
	v_fmac_f32_e32 v4, 0xba800000, v43
	v_pk_mov_b32 v[54:55], v[44:45], v[14:15] op_sel:[1,0]
	v_mov_b32_e32 v45, v15
	v_pk_mov_b32 v[14:15], v[48:49], v[46:47] op_sel:[1,0]
	v_mov_b32_e32 v49, v47
	v_fmamk_f32 v7, v43, 0xba800000, v7
	v_fmamk_f32 v5, v43, 0xba800000, v5
	v_mul_f32_e32 v50, v4, v4
	v_mul_f32_e32 v52, v6, v6
	v_pk_add_f32 v[44:45], v[54:55], v[44:45]
	v_pk_add_f32 v[14:15], v[14:15], v[48:49]
	v_fmamk_f32 v3, v43, 0xba800000, v3
	v_fmamk_f32 v2, v43, 0xba800000, v2
	v_fmamk_f32 v1, v43, 0xba800000, v1
	v_fmac_f32_e32 v0, 0xba800000, v43
	v_pk_fma_f32 v[46:47], v[4:5], v[4:5], v[50:51] op_sel_hi:[1,1,0]
	v_pk_fma_f32 v[50:51], v[6:7], v[6:7], v[52:53] op_sel_hi:[1,1,0]
	v_pk_add_f32 v[44:45], v[44:45], v[44:45] op_sel_hi:[0,1]
	v_pk_add_f32 v[14:15], v[14:15], v[14:15] op_sel_hi:[0,1]
	v_mul_f32_e32 v46, v0, v0
	v_mul_f32_e32 v50, v1, v1
	v_mul_f32_e32 v44, v2, v2
	v_mul_f32_e32 v14, v3, v3
	v_pk_add_f32 v[46:47], v[46:47], v[50:51]
	v_pk_add_f32 v[14:15], v[44:45], v[14:15]
	s_nop 0
	v_pk_add_f32 v[14:15], v[46:47], v[14:15]
	s_nop 0
	v_add_f32_e32 v14, v14, v15
	s_nop 1
	v_add_f32_dpp v14, v14, v14 quad_perm:[1,0,3,2] row_mask:0xf bank_mask:0xf
	s_nop 1
	v_add_f32_dpp v14, v14, v14 quad_perm:[2,3,0,1] row_mask:0xf bank_mask:0xf
	s_nop 1
	v_add_f32_dpp v14, v14, v14 row_half_mirror row_mask:0xf bank_mask:0xf
	s_nop 1
	v_add_f32_dpp v14, v14, v14 row_mirror row_mask:0xf bank_mask:0xf
	v_mov_b32_e32 v15, v14
	s_nop 1
	v_permlane16_swap_b32 v14, v15
	v_add_f32_e32 v14, v14, v15
	v_mov_b32_e32 v15, v14
	s_nop 1
	v_permlane32_swap_b32 v14, v15
	v_add_f32_e32 v14, v14, v15
	v_fmamk_f32 v14, v14, 0x3a800000, v40
	v_mul_f32_e32 v15, 0x4b800000, v14
	v_cmp_gt_f32_e32 vcc, s6, v14
	s_nop 1
	v_cndmask_b32_e32 v14, v14, v15, vcc
	v_rsq_f32_e32 v14, v14
	s_nop 0
	v_mul_f32_e32 v15, 0x45800000, v14
	v_cndmask_b32_e32 v14, v14, v15, vcc
	s_and_saveexec_b64 s[4:5], s[10:11]
	s_cbranch_execz .LBB0_936
	v_lshl_add_u64 v[46:47], s[90:91], 0, v[20:21]
	v_add_co_u32_e32 v46, vcc, 0x1fe00000, v46
	v_mul_f32_e32 v44, 0x3a800000, v43
	s_nop 0
	v_addc_co_u32_e32 v47, vcc, 0, v47, vcc
	v_mov_b32_e32 v45, v14
	global_store_dwordx2 v[46:47], v[44:45], off
	s_branch .LBB0_936

.LBB0_1257:
	s_mov_b32 s4, 0x3e0f83e1
	v_mul_hi_i32 v0, v53, s4
	v_lshrrev_b32_e32 v1, 31, v0
	v_ashrrev_i32_e32 v0, 11, v0
	v_add_u32_e32 v54, v0, v1
	v_mad_i32_i24 v1, v54, s2, v53
	s_movk_i32 s4, 0x100
	v_cmp_gt_i32_e64 s[12:13], s4, v1
	v_cmp_lt_i32_e32 vcc, s6, v1
	s_and_saveexec_b64 s[4:5], vcc
	s_xor_b64 s[4:5], exec, s[4:5]
	v_mul_i32_i24_e32 v0, 0xffffdf00, v54
	v_lshl_add_u32 v0, v54, 13, v0
	v_add3_u32 v0, v53, v0, s7
	s_or_saveexec_b64 s[4:5], s[4:5]
	v_readlane_b32 s16, v254, 28
	v_readlane_b32 s20, v254, 32
	v_readlane_b32 s21, v254, 33
	v_readlane_b32 s17, v254, 29
	v_readlane_b32 s18, v254, 30
	v_mov_b64_e32 v[2:3], s[20:21]
	v_readlane_b32 s19, v254, 31
	v_readlane_b32 s22, v254, 34
	v_readlane_b32 s23, v254, 35
	s_xor_b64 exec, exec, s[4:5]
	v_lshl_add_u32 v0, v54, 8, v1
	v_mov_b64_e32 v[2:3], s[70:71]
	s_or_b64 exec, exec, s[4:5]
	v_ashrrev_i32_e32 v1, 31, v0
	v_lshlrev_b64 v[0:1], 12, v[0:1]
	v_lshl_add_u64 v[0:1], v[2:3], 0, v[0:1]
	v_lshl_add_u64 v[0:1], v[0:1], 0, v[36:37]
	global_load_dwordx4 v[12:15], v[0:1], off nt
	global_load_dwordx4 v[8:11], v[0:1], off offset:1024 nt
	global_load_dwordx4 v[4:7], v[0:1], off offset:2048 nt
	s_nop 0
	global_load_dwordx4 v[0:3], v[0:1], off offset:3072 nt
	s_waitcnt vmcnt(3)
	v_mov_b32_e32 v44, v13
	v_mov_b32_e32 v45, v14
	v_mov_b32_e32 v56, v12
	v_mov_b32_e32 v57, v15
	s_waitcnt vmcnt(2)
	v_mov_b32_e32 v58, v9
	v_mov_b32_e32 v59, v10
	v_mov_b32_e32 v60, v8
	v_mov_b32_e32 v61, v11
	v_pk_add_f32 v[44:45], v[44:45], v[56:57]
	v_pk_add_f32 v[56:57], v[58:59], v[60:61]
	v_add_f32_e32 v55, v44, v45
	v_pk_add_f32 v[44:45], v[56:57], v[56:57] op_sel:[0,1] op_sel_hi:[1,0]
	s_waitcnt vmcnt(1)
	v_add_f32_e32 v62, v4, v5
	v_add_f32_e32 v64, v6, v7
	s_waitcnt vmcnt(0)
	v_mov_b32_e32 v67, v0
	v_mov_b32_e32 v63, v2
	v_mov_b32_e32 v65, v3
	v_add_f32_e32 v66, 0, v55
	v_mov_b32_e32 v45, v1
	v_pk_add_f32 v[58:59], v[62:63], v[64:65]
	v_pk_add_f32 v[44:45], v[66:67], v[44:45]
	s_nop 0
	v_pk_add_f32 v[44:45], v[44:45], v[58:59]
	s_nop 0
	v_add_f32_e32 v44, v44, v45
	s_nop 1
	v_add_f32_dpp v44, v44, v44 quad_perm:[1,0,3,2] row_mask:0xf bank_mask:0xf
	s_nop 1
	v_add_f32_dpp v44, v44, v44 quad_perm:[2,3,0,1] row_mask:0xf bank_mask:0xf
	s_nop 1
	v_add_f32_dpp v44, v44, v44 row_half_mirror row_mask:0xf bank_mask:0xf
	s_nop 1
	v_add_f32_dpp v44, v44, v44 row_mirror row_mask:0xf bank_mask:0xf
	v_mov_b32_e32 v45, v44
	s_nop 1
	v_permlane16_swap_b32 v44, v45
	v_add_f32_e32 v44, v44, v45
	v_mov_b32_e32 v45, v44
	s_nop 1
	v_permlane32_swap_b32 v44, v45
	v_add_f32_e32 v55, v44, v45
	v_fmamk_f32 v45, v55, 0xba800000, v15
	v_fmamk_f32 v44, v55, 0xba800000, v14
	v_fmamk_f32 v13, v55, 0xba800000, v13
	v_fmac_f32_e32 v12, 0xba800000, v55
	v_fmamk_f32 v11, v55, 0xba800000, v11
	v_fmamk_f32 v10, v55, 0xba800000, v10
	v_fmamk_f32 v9, v55, 0xba800000, v9
	v_fmac_f32_e32 v8, 0xba800000, v55
	v_pk_mul_f32 v[14:15], v[44:45], v[44:45]
	v_pk_mul_f32 v[56:57], v[12:13], v[12:13]
	v_pk_mul_f32 v[58:59], v[10:11], v[10:11]
	v_pk_mul_f32 v[60:61], v[8:9], v[8:9]
	v_fmamk_f32 v6, v55, 0xba800000, v6
	v_fmac_f32_e32 v4, 0xba800000, v55
	v_pk_mov_b32 v[66:67], v[56:57], v[14:15] op_sel:[1,0]
	v_mov_b32_e32 v57, v15
	v_pk_mov_b32 v[14:15], v[60:61], v[58:59] op_sel:[1,0]
	v_mov_b32_e32 v61, v59
	v_fmamk_f32 v7, v55, 0xba800000, v7
	v_fmamk_f32 v5, v55, 0xba800000, v5
	v_mul_f32_e32 v62, v4, v4
	v_mul_f32_e32 v64, v6, v6
	v_pk_add_f32 v[56:57], v[66:67], v[56:57]
	v_pk_add_f32 v[14:15], v[14:15], v[60:61]
	v_fmamk_f32 v3, v55, 0xba800000, v3
	v_fmamk_f32 v2, v55, 0xba800000, v2
	v_fmamk_f32 v1, v55, 0xba800000, v1
	v_fmac_f32_e32 v0, 0xba800000, v55
	v_pk_fma_f32 v[58:59], v[4:5], v[4:5], v[62:63] op_sel_hi:[1,1,0]
	v_pk_fma_f32 v[62:63], v[6:7], v[6:7], v[64:65] op_sel_hi:[1,1,0]
	v_pk_add_f32 v[56:57], v[56:57], v[56:57] op_sel_hi:[0,1]
	v_pk_add_f32 v[14:15], v[14:15], v[14:15] op_sel_hi:[0,1]
	v_mul_f32_e32 v58, v0, v0
	v_mul_f32_e32 v62, v1, v1
	v_mul_f32_e32 v56, v2, v2
	v_mul_f32_e32 v14, v3, v3
	v_pk_add_f32 v[58:59], v[58:59], v[62:63]
	v_pk_add_f32 v[14:15], v[56:57], v[14:15]
	s_nop 0
	v_pk_add_f32 v[14:15], v[58:59], v[14:15]
	s_nop 0
	v_add_f32_e32 v14, v14, v15
	s_nop 1
	v_add_f32_dpp v14, v14, v14 quad_perm:[1,0,3,2] row_mask:0xf bank_mask:0xf
	s_nop 1
	v_add_f32_dpp v14, v14, v14 quad_perm:[2,3,0,1] row_mask:0xf bank_mask:0xf
	s_nop 1
	v_add_f32_dpp v14, v14, v14 row_half_mirror row_mask:0xf bank_mask:0xf
	s_nop 1
	v_add_f32_dpp v14, v14, v14 row_mirror row_mask:0xf bank_mask:0xf
	v_mov_b32_e32 v15, v14
	s_nop 1
	v_permlane16_swap_b32 v14, v15
	v_add_f32_e32 v14, v14, v15
	v_mov_b32_e32 v15, v14
	s_nop 1
	v_permlane32_swap_b32 v14, v15
	v_add_f32_e32 v14, v14, v15
	v_fmamk_f32 v14, v14, 0x3a800000, v52
	v_mul_f32_e32 v15, 0x4b800000, v14
	v_cmp_gt_f32_e32 vcc, s26, v14
	s_nop 1
	v_cndmask_b32_e32 v14, v14, v15, vcc
	v_rsq_f32_e32 v14, v14
	s_nop 0
	v_mul_f32_e32 v15, 0x45800000, v14
	v_cndmask_b32_e32 v14, v14, v15, vcc
	s_and_saveexec_b64 s[4:5], s[10:11]
	s_cbranch_execz .LBB0_1256
	v_readlane_b32 s16, v254, 28
	v_readlane_b32 s22, v254, 34
	v_readlane_b32 s23, v254, 35
	v_mul_f32_e32 v56, 0x3a800000, v55
	v_mov_b32_e32 v57, v14
	v_lshl_add_u64 v[58:59], s[22:23], 0, v[32:33]
	v_add_co_u32_e32 v58, vcc, 0x1fe00000, v58
	v_readlane_b32 s17, v254, 29
	s_nop 0
	v_addc_co_u32_e32 v59, vcc, 0, v59, vcc
	v_readlane_b32 s18, v254, 30
	v_readlane_b32 s19, v254, 31
	v_readlane_b32 s20, v254, 32
	v_readlane_b32 s21, v254, 33
	global_store_dwordx2 v[58:59], v[56:57], off
	s_branch .LBB0_1256

.LBB0_1847:
	v_mul_hi_i32 v0, v53, s6
	v_lshrrev_b32_e32 v1, 31, v0
	v_ashrrev_i32_e32 v0, 11, v0
	v_add_u32_e32 v54, v0, v1
	v_mad_i32_i24 v1, v54, s7, v53
	v_cmp_gt_i32_e64 s[10:11], s2, v1
	v_cmp_lt_i32_e32 vcc, s28, v1
	s_and_saveexec_b64 s[4:5], vcc
	s_xor_b64 s[4:5], exec, s[4:5]
	v_mul_i32_i24_e32 v0, 0xffffdf00, v54
	v_lshl_add_u32 v0, v54, 13, v0
	v_add3_u32 v0, v53, v0, s29
	s_or_saveexec_b64 s[4:5], s[4:5]
	v_readlane_b32 s16, v254, 28
	v_readlane_b32 s20, v254, 32
	v_readlane_b32 s21, v254, 33
	v_readlane_b32 s17, v254, 29
	v_readlane_b32 s18, v254, 30
	v_mov_b64_e32 v[2:3], s[20:21]
	v_readlane_b32 s19, v254, 31
	v_readlane_b32 s22, v254, 34
	v_readlane_b32 s23, v254, 35
	s_xor_b64 exec, exec, s[4:5]
	v_lshl_add_u32 v0, v54, 8, v1
	v_mov_b64_e32 v[2:3], s[70:71]
	s_or_b64 exec, exec, s[4:5]
	v_ashrrev_i32_e32 v1, 31, v0
	v_lshlrev_b64 v[0:1], 12, v[0:1]
	v_lshl_add_u64 v[0:1], v[2:3], 0, v[0:1]
	v_lshl_add_u64 v[0:1], v[0:1], 0, v[36:37]
	global_load_dwordx4 v[12:15], v[0:1], off nt
	global_load_dwordx4 v[8:11], v[0:1], off offset:1024 nt
	global_load_dwordx4 v[4:7], v[0:1], off offset:2048 nt
	s_nop 0
	global_load_dwordx4 v[0:3], v[0:1], off offset:3072 nt
	s_waitcnt vmcnt(3)
	v_mov_b32_e32 v44, v13
	v_mov_b32_e32 v45, v14
	v_mov_b32_e32 v56, v12
	v_mov_b32_e32 v57, v15
	s_waitcnt vmcnt(2)
	v_mov_b32_e32 v58, v9
	v_mov_b32_e32 v59, v10
	v_mov_b32_e32 v60, v8
	v_mov_b32_e32 v61, v11
	v_pk_add_f32 v[44:45], v[44:45], v[56:57]
	v_pk_add_f32 v[56:57], v[58:59], v[60:61]
	v_add_f32_e32 v55, v44, v45
	v_pk_add_f32 v[44:45], v[56:57], v[56:57] op_sel:[0,1] op_sel_hi:[1,0]
	s_waitcnt vmcnt(1)
	v_add_f32_e32 v62, v4, v5
	v_add_f32_e32 v64, v6, v7
	s_waitcnt vmcnt(0)
	v_mov_b32_e32 v67, v0
	v_mov_b32_e32 v63, v2
	v_mov_b32_e32 v65, v3
	v_add_f32_e32 v66, 0, v55
	v_mov_b32_e32 v45, v1
	v_pk_add_f32 v[58:59], v[62:63], v[64:65]
	v_pk_add_f32 v[44:45], v[66:67], v[44:45]
	s_nop 0
	v_pk_add_f32 v[44:45], v[44:45], v[58:59]
	s_nop 0
	v_add_f32_e32 v44, v44, v45
	s_nop 1
	v_add_f32_dpp v44, v44, v44 quad_perm:[1,0,3,2] row_mask:0xf bank_mask:0xf
	s_nop 1
	v_add_f32_dpp v44, v44, v44 quad_perm:[2,3,0,1] row_mask:0xf bank_mask:0xf
	s_nop 1
	v_add_f32_dpp v44, v44, v44 row_half_mirror row_mask:0xf bank_mask:0xf
	s_nop 1
	v_add_f32_dpp v44, v44, v44 row_mirror row_mask:0xf bank_mask:0xf
	v_mov_b32_e32 v45, v44
	s_nop 1
	v_permlane16_swap_b32 v44, v45
	v_add_f32_e32 v44, v44, v45
	v_mov_b32_e32 v45, v44
	s_nop 1
	v_permlane32_swap_b32 v44, v45
	v_add_f32_e32 v55, v44, v45
	v_fmamk_f32 v45, v55, 0xba800000, v15
	v_fmamk_f32 v44, v55, 0xba800000, v14
	v_fmamk_f32 v13, v55, 0xba800000, v13
	v_fmac_f32_e32 v12, 0xba800000, v55
	v_fmamk_f32 v11, v55, 0xba800000, v11
	v_fmamk_f32 v10, v55, 0xba800000, v10
	v_fmamk_f32 v9, v55, 0xba800000, v9
	v_fmac_f32_e32 v8, 0xba800000, v55
	v_pk_mul_f32 v[14:15], v[44:45], v[44:45]
	v_pk_mul_f32 v[56:57], v[12:13], v[12:13]
	v_pk_mul_f32 v[58:59], v[10:11], v[10:11]
	v_pk_mul_f32 v[60:61], v[8:9], v[8:9]
	v_fmamk_f32 v6, v55, 0xba800000, v6
	v_fmac_f32_e32 v4, 0xba800000, v55
	v_pk_mov_b32 v[66:67], v[56:57], v[14:15] op_sel:[1,0]
	v_mov_b32_e32 v57, v15
	v_pk_mov_b32 v[14:15], v[60:61], v[58:59] op_sel:[1,0]
	v_mov_b32_e32 v61, v59
	v_fmamk_f32 v7, v55, 0xba800000, v7
	v_fmamk_f32 v5, v55, 0xba800000, v5
	v_mul_f32_e32 v62, v4, v4
	v_mul_f32_e32 v64, v6, v6
	v_pk_add_f32 v[56:57], v[66:67], v[56:57]
	v_pk_add_f32 v[14:15], v[14:15], v[60:61]
	v_fmamk_f32 v3, v55, 0xba800000, v3
	v_fmamk_f32 v2, v55, 0xba800000, v2
	v_fmamk_f32 v1, v55, 0xba800000, v1
	v_fmac_f32_e32 v0, 0xba800000, v55
	v_pk_fma_f32 v[58:59], v[4:5], v[4:5], v[62:63] op_sel_hi:[1,1,0]
	v_pk_fma_f32 v[62:63], v[6:7], v[6:7], v[64:65] op_sel_hi:[1,1,0]
	v_pk_add_f32 v[56:57], v[56:57], v[56:57] op_sel_hi:[0,1]
	v_pk_add_f32 v[14:15], v[14:15], v[14:15] op_sel_hi:[0,1]
	v_mul_f32_e32 v58, v0, v0
	v_mul_f32_e32 v62, v1, v1
	v_mul_f32_e32 v56, v2, v2
	v_mul_f32_e32 v14, v3, v3
	v_pk_add_f32 v[58:59], v[58:59], v[62:63]
	v_pk_add_f32 v[14:15], v[56:57], v[14:15]
	s_nop 0
	v_pk_add_f32 v[14:15], v[58:59], v[14:15]
	s_nop 0
	v_add_f32_e32 v14, v14, v15
	s_nop 1
	v_add_f32_dpp v14, v14, v14 quad_perm:[1,0,3,2] row_mask:0xf bank_mask:0xf
	s_nop 1
	v_add_f32_dpp v14, v14, v14 quad_perm:[2,3,0,1] row_mask:0xf bank_mask:0xf
	s_nop 1
	v_add_f32_dpp v14, v14, v14 row_half_mirror row_mask:0xf bank_mask:0xf
	s_nop 1
	v_add_f32_dpp v14, v14, v14 row_mirror row_mask:0xf bank_mask:0xf
	v_mov_b32_e32 v15, v14
	s_nop 1
	v_permlane16_swap_b32 v14, v15
	v_add_f32_e32 v14, v14, v15
	v_mov_b32_e32 v15, v14
	s_nop 1
	v_permlane32_swap_b32 v14, v15
	v_add_f32_e32 v14, v14, v15
	v_fmamk_f32 v14, v14, 0x3a800000, v52
	v_mul_f32_e32 v15, 0x4b800000, v14
	v_cmp_gt_f32_e32 vcc, s30, v14
	s_nop 1
	v_cndmask_b32_e32 v14, v14, v15, vcc
	v_rsq_f32_e32 v14, v14
	s_nop 0
	v_mul_f32_e32 v15, 0x45800000, v14
	v_cndmask_b32_e32 v14, v14, v15, vcc
	s_and_saveexec_b64 s[4:5], s[8:9]
	s_cbranch_execz .LBB0_1846
	v_readlane_b32 s16, v254, 28
	v_readlane_b32 s22, v254, 34
	v_readlane_b32 s23, v254, 35
	v_mul_f32_e32 v56, 0x3a800000, v55
	v_mov_b32_e32 v57, v14
	v_lshl_add_u64 v[58:59], s[22:23], 0, v[32:33]
	v_add_co_u32_e32 v58, vcc, 0x1fe00000, v58
	v_readlane_b32 s17, v254, 29
	s_nop 0
	v_addc_co_u32_e32 v59, vcc, 0, v59, vcc
	v_readlane_b32 s18, v254, 30
	v_readlane_b32 s19, v254, 31
	v_readlane_b32 s20, v254, 32
	v_readlane_b32 s21, v254, 33
	global_store_dwordx2 v[58:59], v[56:57], off
	s_branch .LBB0_1846

.LBB0_2075:
	v_mul_hi_i32 v0, v53, s6
	v_lshrrev_b32_e32 v1, 31, v0
	v_ashrrev_i32_e32 v0, 11, v0
	v_add_u32_e32 v54, v0, v1
	v_mad_i32_i24 v1, v54, s7, v53
	v_cmp_gt_i32_e64 s[12:13], s2, v1
	v_cmp_lt_i32_e32 vcc, s8, v1
	s_and_saveexec_b64 s[4:5], vcc
	s_xor_b64 s[4:5], exec, s[4:5]
	v_mul_i32_i24_e32 v0, 0xffffdf00, v54
	v_lshl_add_u32 v0, v54, 13, v0
	v_add3_u32 v0, v53, v0, s9
	s_or_saveexec_b64 s[4:5], s[4:5]
	v_readlane_b32 s36, v254, 28
	v_readlane_b32 s40, v254, 32
	v_readlane_b32 s41, v254, 33
	v_readlane_b32 s37, v254, 29
	v_readlane_b32 s38, v254, 30
	v_mov_b64_e32 v[2:3], s[40:41]
	v_readlane_b32 s39, v254, 31
	v_readlane_b32 s42, v254, 34
	v_readlane_b32 s43, v254, 35
	s_xor_b64 exec, exec, s[4:5]
	v_lshl_add_u32 v0, v54, 8, v1
	v_mov_b64_e32 v[2:3], s[70:71]
	s_or_b64 exec, exec, s[4:5]
	v_ashrrev_i32_e32 v1, 31, v0
	v_lshlrev_b64 v[0:1], 12, v[0:1]
	v_lshl_add_u64 v[0:1], v[2:3], 0, v[0:1]
	v_lshl_add_u64 v[0:1], v[0:1], 0, v[36:37]
	global_load_dwordx4 v[12:15], v[0:1], off nt
	global_load_dwordx4 v[8:11], v[0:1], off offset:1024 nt
	global_load_dwordx4 v[4:7], v[0:1], off offset:2048 nt
	s_nop 0
	global_load_dwordx4 v[0:3], v[0:1], off offset:3072 nt
	s_waitcnt vmcnt(3)
	v_mov_b32_e32 v44, v13
	v_mov_b32_e32 v45, v14
	v_mov_b32_e32 v56, v12
	v_mov_b32_e32 v57, v15
	s_waitcnt vmcnt(2)
	v_mov_b32_e32 v58, v9
	v_mov_b32_e32 v59, v10
	v_mov_b32_e32 v60, v8
	v_mov_b32_e32 v61, v11
	v_pk_add_f32 v[44:45], v[44:45], v[56:57]
	v_pk_add_f32 v[56:57], v[58:59], v[60:61]
	v_add_f32_e32 v55, v44, v45
	v_pk_add_f32 v[44:45], v[56:57], v[56:57] op_sel:[0,1] op_sel_hi:[1,0]
	s_waitcnt vmcnt(1)
	v_add_f32_e32 v62, v4, v5
	v_add_f32_e32 v64, v6, v7
	s_waitcnt vmcnt(0)
	v_mov_b32_e32 v67, v0
	v_mov_b32_e32 v63, v2
	v_mov_b32_e32 v65, v3
	v_add_f32_e32 v66, 0, v55
	v_mov_b32_e32 v45, v1
	v_pk_add_f32 v[58:59], v[62:63], v[64:65]
	v_pk_add_f32 v[44:45], v[66:67], v[44:45]
	s_nop 0
	v_pk_add_f32 v[44:45], v[44:45], v[58:59]
	s_nop 0
	v_add_f32_e32 v44, v44, v45
	s_nop 1
	v_add_f32_dpp v44, v44, v44 quad_perm:[1,0,3,2] row_mask:0xf bank_mask:0xf
	s_nop 1
	v_add_f32_dpp v44, v44, v44 quad_perm:[2,3,0,1] row_mask:0xf bank_mask:0xf
	s_nop 1
	v_add_f32_dpp v44, v44, v44 row_half_mirror row_mask:0xf bank_mask:0xf
	s_nop 1
	v_add_f32_dpp v44, v44, v44 row_mirror row_mask:0xf bank_mask:0xf
	v_mov_b32_e32 v45, v44
	s_nop 1
	v_permlane16_swap_b32 v44, v45
	v_add_f32_e32 v44, v44, v45
	v_mov_b32_e32 v45, v44
	s_nop 1
	v_permlane32_swap_b32 v44, v45
	v_add_f32_e32 v55, v44, v45
	v_fmamk_f32 v45, v55, 0xba800000, v15
	v_fmamk_f32 v44, v55, 0xba800000, v14
	v_fmamk_f32 v13, v55, 0xba800000, v13
	v_fmac_f32_e32 v12, 0xba800000, v55
	v_fmamk_f32 v11, v55, 0xba800000, v11
	v_fmamk_f32 v10, v55, 0xba800000, v10
	v_fmamk_f32 v9, v55, 0xba800000, v9
	v_fmac_f32_e32 v8, 0xba800000, v55
	v_pk_mul_f32 v[14:15], v[44:45], v[44:45]
	v_pk_mul_f32 v[56:57], v[12:13], v[12:13]
	v_pk_mul_f32 v[58:59], v[10:11], v[10:11]
	v_pk_mul_f32 v[60:61], v[8:9], v[8:9]
	v_fmamk_f32 v6, v55, 0xba800000, v6
	v_fmac_f32_e32 v4, 0xba800000, v55
	v_pk_mov_b32 v[66:67], v[56:57], v[14:15] op_sel:[1,0]
	v_mov_b32_e32 v57, v15
	v_pk_mov_b32 v[14:15], v[60:61], v[58:59] op_sel:[1,0]
	v_mov_b32_e32 v61, v59
	v_fmamk_f32 v7, v55, 0xba800000, v7
	v_fmamk_f32 v5, v55, 0xba800000, v5
	v_mul_f32_e32 v62, v4, v4
	v_mul_f32_e32 v64, v6, v6
	v_pk_add_f32 v[56:57], v[66:67], v[56:57]
	v_pk_add_f32 v[14:15], v[14:15], v[60:61]
	v_fmamk_f32 v3, v55, 0xba800000, v3
	v_fmamk_f32 v2, v55, 0xba800000, v2
	v_fmamk_f32 v1, v55, 0xba800000, v1
	v_fmac_f32_e32 v0, 0xba800000, v55
	v_pk_fma_f32 v[58:59], v[4:5], v[4:5], v[62:63] op_sel_hi:[1,1,0]
	v_pk_fma_f32 v[62:63], v[6:7], v[6:7], v[64:65] op_sel_hi:[1,1,0]
	v_pk_add_f32 v[56:57], v[56:57], v[56:57] op_sel_hi:[0,1]
	v_pk_add_f32 v[14:15], v[14:15], v[14:15] op_sel_hi:[0,1]
	v_mul_f32_e32 v58, v0, v0
	v_mul_f32_e32 v62, v1, v1
	v_mul_f32_e32 v56, v2, v2
	v_mul_f32_e32 v14, v3, v3
	v_pk_add_f32 v[58:59], v[58:59], v[62:63]
	v_pk_add_f32 v[14:15], v[56:57], v[14:15]
	s_nop 0
	v_pk_add_f32 v[14:15], v[58:59], v[14:15]
	s_nop 0
	v_add_f32_e32 v14, v14, v15
	s_nop 1
	v_add_f32_dpp v14, v14, v14 quad_perm:[1,0,3,2] row_mask:0xf bank_mask:0xf
	s_nop 1
	v_add_f32_dpp v14, v14, v14 quad_perm:[2,3,0,1] row_mask:0xf bank_mask:0xf
	s_nop 1
	v_add_f32_dpp v14, v14, v14 row_half_mirror row_mask:0xf bank_mask:0xf
	s_nop 1
	v_add_f32_dpp v14, v14, v14 row_mirror row_mask:0xf bank_mask:0xf
	v_mov_b32_e32 v15, v14
	s_nop 1
	v_permlane16_swap_b32 v14, v15
	v_add_f32_e32 v14, v14, v15
	v_mov_b32_e32 v15, v14
	s_nop 1
	v_permlane32_swap_b32 v14, v15
	v_add_f32_e32 v14, v14, v15
	v_fmamk_f32 v14, v14, 0x3a800000, v52
	v_mul_f32_e32 v15, 0x4b800000, v14
	v_cmp_gt_f32_e32 vcc, s28, v14
	s_nop 1
	v_cndmask_b32_e32 v14, v14, v15, vcc
	v_rsq_f32_e32 v14, v14
	s_nop 0
	v_mul_f32_e32 v15, 0x45800000, v14
	v_cndmask_b32_e32 v14, v14, v15, vcc
	s_and_saveexec_b64 s[4:5], s[10:11]
	s_cbranch_execz .LBB0_2074
	v_readlane_b32 s36, v254, 28
	v_readlane_b32 s42, v254, 34
	v_readlane_b32 s43, v254, 35
	v_mul_f32_e32 v56, 0x3a800000, v55
	v_mov_b32_e32 v57, v14
	v_lshl_add_u64 v[58:59], s[42:43], 0, v[32:33]
	v_add_co_u32_e32 v58, vcc, 0x1fe00000, v58
	v_readlane_b32 s37, v254, 29
	s_nop 0
	v_addc_co_u32_e32 v59, vcc, 0, v59, vcc
	v_readlane_b32 s38, v254, 30
	v_readlane_b32 s39, v254, 31
	v_readlane_b32 s40, v254, 32
	v_readlane_b32 s41, v254, 33
	global_store_dwordx2 v[58:59], v[56:57], off
	s_branch .LBB0_2074

.LBB0_2882:
	v_mul_hi_i32 v0, v53, s6
	v_lshrrev_b32_e32 v1, 31, v0
	v_ashrrev_i32_e32 v0, 11, v0
	v_add_u32_e32 v54, v0, v1
	v_mad_i32_i24 v1, v54, s7, v53
	v_cmp_gt_i32_e64 s[12:13], s2, v1
	v_cmp_lt_i32_e32 vcc, s8, v1
	s_and_saveexec_b64 s[4:5], vcc
	s_xor_b64 s[4:5], exec, s[4:5]
	v_mul_i32_i24_e32 v0, 0xffffdf00, v54
	v_lshl_add_u32 v0, v54, 13, v0
	v_add3_u32 v0, v53, v0, s9
	s_or_saveexec_b64 s[4:5], s[4:5]
	v_mov_b64_e32 v[2:3], s[88:89]
	s_xor_b64 exec, exec, s[4:5]
	v_lshl_add_u32 v0, v54, 8, v1
	v_mov_b64_e32 v[2:3], s[70:71]
	s_or_b64 exec, exec, s[4:5]
	v_ashrrev_i32_e32 v1, 31, v0
	v_lshlrev_b64 v[0:1], 12, v[0:1]
	v_lshl_add_u64 v[0:1], v[2:3], 0, v[0:1]
	v_lshl_add_u64 v[0:1], v[0:1], 0, v[36:37]
	global_load_dwordx4 v[12:15], v[0:1], off nt
	global_load_dwordx4 v[8:11], v[0:1], off offset:1024 nt
	global_load_dwordx4 v[4:7], v[0:1], off offset:2048 nt
	s_nop 0
	global_load_dwordx4 v[0:3], v[0:1], off offset:3072 nt
	s_waitcnt vmcnt(3)
	v_mov_b32_e32 v44, v13
	v_mov_b32_e32 v45, v14
	v_mov_b32_e32 v56, v12
	v_mov_b32_e32 v57, v15
	s_waitcnt vmcnt(2)
	v_mov_b32_e32 v58, v9
	v_mov_b32_e32 v59, v10
	v_mov_b32_e32 v60, v8
	v_mov_b32_e32 v61, v11
	v_pk_add_f32 v[44:45], v[44:45], v[56:57]
	v_pk_add_f32 v[56:57], v[58:59], v[60:61]
	v_add_f32_e32 v55, v44, v45
	v_pk_add_f32 v[44:45], v[56:57], v[56:57] op_sel:[0,1] op_sel_hi:[1,0]
	s_waitcnt vmcnt(1)
	v_add_f32_e32 v62, v4, v5
	v_add_f32_e32 v64, v6, v7
	s_waitcnt vmcnt(0)
	v_mov_b32_e32 v67, v0
	v_mov_b32_e32 v63, v2
	v_mov_b32_e32 v65, v3
	v_add_f32_e32 v66, 0, v55
	v_mov_b32_e32 v45, v1
	v_pk_add_f32 v[58:59], v[62:63], v[64:65]
	v_pk_add_f32 v[44:45], v[66:67], v[44:45]
	s_nop 0
	v_pk_add_f32 v[44:45], v[44:45], v[58:59]
	s_nop 0
	v_add_f32_e32 v44, v44, v45
	s_nop 1
	v_add_f32_dpp v44, v44, v44 quad_perm:[1,0,3,2] row_mask:0xf bank_mask:0xf
	s_nop 1
	v_add_f32_dpp v44, v44, v44 quad_perm:[2,3,0,1] row_mask:0xf bank_mask:0xf
	s_nop 1
	v_add_f32_dpp v44, v44, v44 row_half_mirror row_mask:0xf bank_mask:0xf
	s_nop 1
	v_add_f32_dpp v44, v44, v44 row_mirror row_mask:0xf bank_mask:0xf
	v_mov_b32_e32 v45, v44
	s_nop 1
	v_permlane16_swap_b32 v44, v45
	v_add_f32_e32 v44, v44, v45
	v_mov_b32_e32 v45, v44
	s_nop 1
	v_permlane32_swap_b32 v44, v45
	v_add_f32_e32 v55, v44, v45
	v_fmamk_f32 v45, v55, 0xba800000, v15
	v_fmamk_f32 v44, v55, 0xba800000, v14
	v_fmamk_f32 v13, v55, 0xba800000, v13
	v_fmac_f32_e32 v12, 0xba800000, v55
	v_fmamk_f32 v11, v55, 0xba800000, v11
	v_fmamk_f32 v10, v55, 0xba800000, v10
	v_fmamk_f32 v9, v55, 0xba800000, v9
	v_fmac_f32_e32 v8, 0xba800000, v55
	v_pk_mul_f32 v[14:15], v[44:45], v[44:45]
	v_pk_mul_f32 v[56:57], v[12:13], v[12:13]
	v_pk_mul_f32 v[58:59], v[10:11], v[10:11]
	v_pk_mul_f32 v[60:61], v[8:9], v[8:9]
	v_fmamk_f32 v6, v55, 0xba800000, v6
	v_fmac_f32_e32 v4, 0xba800000, v55
	v_pk_mov_b32 v[66:67], v[56:57], v[14:15] op_sel:[1,0]
	v_mov_b32_e32 v57, v15
	v_pk_mov_b32 v[14:15], v[60:61], v[58:59] op_sel:[1,0]
	v_mov_b32_e32 v61, v59
	v_fmamk_f32 v7, v55, 0xba800000, v7
	v_fmamk_f32 v5, v55, 0xba800000, v5
	v_mul_f32_e32 v62, v4, v4
	v_mul_f32_e32 v64, v6, v6
	v_pk_add_f32 v[56:57], v[66:67], v[56:57]
	v_pk_add_f32 v[14:15], v[14:15], v[60:61]
	v_fmamk_f32 v3, v55, 0xba800000, v3
	v_fmamk_f32 v2, v55, 0xba800000, v2
	v_fmamk_f32 v1, v55, 0xba800000, v1
	v_fmac_f32_e32 v0, 0xba800000, v55
	v_pk_fma_f32 v[58:59], v[4:5], v[4:5], v[62:63] op_sel_hi:[1,1,0]
	v_pk_fma_f32 v[62:63], v[6:7], v[6:7], v[64:65] op_sel_hi:[1,1,0]
	v_pk_add_f32 v[56:57], v[56:57], v[56:57] op_sel_hi:[0,1]
	v_pk_add_f32 v[14:15], v[14:15], v[14:15] op_sel_hi:[0,1]
	v_mul_f32_e32 v58, v0, v0
	v_mul_f32_e32 v62, v1, v1
	v_mul_f32_e32 v56, v2, v2
	v_mul_f32_e32 v14, v3, v3
	v_pk_add_f32 v[58:59], v[58:59], v[62:63]
	v_pk_add_f32 v[14:15], v[56:57], v[14:15]
	s_nop 0
	v_pk_add_f32 v[14:15], v[58:59], v[14:15]
	s_nop 0
	v_add_f32_e32 v14, v14, v15
	s_nop 1
	v_add_f32_dpp v14, v14, v14 quad_perm:[1,0,3,2] row_mask:0xf bank_mask:0xf
	s_nop 1
	v_add_f32_dpp v14, v14, v14 quad_perm:[2,3,0,1] row_mask:0xf bank_mask:0xf
	s_nop 1
	v_add_f32_dpp v14, v14, v14 row_half_mirror row_mask:0xf bank_mask:0xf
	s_nop 1
	v_add_f32_dpp v14, v14, v14 row_mirror row_mask:0xf bank_mask:0xf
	v_mov_b32_e32 v15, v14
	s_nop 1
	v_permlane16_swap_b32 v14, v15
	v_add_f32_e32 v14, v14, v15
	v_mov_b32_e32 v15, v14
	s_nop 1
	v_permlane32_swap_b32 v14, v15
	v_add_f32_e32 v14, v14, v15
	v_fmamk_f32 v14, v14, 0x3a800000, v52
	v_mul_f32_e32 v15, 0x4b800000, v14
	v_cmp_gt_f32_e32 vcc, s24, v14
	s_nop 1
	v_cndmask_b32_e32 v14, v14, v15, vcc
	v_rsq_f32_e32 v14, v14
	s_nop 0
	v_mul_f32_e32 v15, 0x45800000, v14
	v_cndmask_b32_e32 v14, v14, v15, vcc
	s_and_saveexec_b64 s[4:5], s[10:11]
	s_cbranch_execz .LBB0_2881
	v_lshl_add_u64 v[58:59], s[90:91], 0, v[32:33]
	v_add_co_u32_e32 v58, vcc, 0x1fe00000, v58
	v_mul_f32_e32 v56, 0x3a800000, v55
	s_nop 0
	v_addc_co_u32_e32 v59, vcc, 0, v59, vcc
	v_mov_b32_e32 v57, v14
	global_store_dwordx2 v[58:59], v[56:57], off
	s_branch .LBB0_2881

.LBB0_3110:
	v_mul_hi_i32 v0, v53, s6
	v_lshrrev_b32_e32 v1, 31, v0
	v_ashrrev_i32_e32 v0, 11, v0
	v_add_u32_e32 v54, v0, v1
	v_mad_i32_i24 v1, v54, s7, v53
	v_cmp_gt_i32_e64 s[10:11], s2, v1
	v_cmp_lt_i32_e32 vcc, s20, v1
	s_and_saveexec_b64 s[4:5], vcc
	s_xor_b64 s[4:5], exec, s[4:5]
	v_mul_i32_i24_e32 v0, 0xffffdf00, v54
	v_lshl_add_u32 v0, v54, 13, v0
	v_add3_u32 v0, v53, v0, s21
	s_or_saveexec_b64 s[4:5], s[4:5]
	v_mov_b64_e32 v[2:3], s[88:89]
	s_xor_b64 exec, exec, s[4:5]
	v_lshl_add_u32 v0, v54, 8, v1
	v_mov_b64_e32 v[2:3], s[70:71]
	s_or_b64 exec, exec, s[4:5]
	v_ashrrev_i32_e32 v1, 31, v0
	v_lshlrev_b64 v[0:1], 12, v[0:1]
	v_lshl_add_u64 v[0:1], v[2:3], 0, v[0:1]
	v_lshl_add_u64 v[0:1], v[0:1], 0, v[36:37]
	global_load_dwordx4 v[12:15], v[0:1], off nt
	global_load_dwordx4 v[8:11], v[0:1], off offset:1024 nt
	global_load_dwordx4 v[4:7], v[0:1], off offset:2048 nt
	s_nop 0
	global_load_dwordx4 v[0:3], v[0:1], off offset:3072 nt
	s_waitcnt vmcnt(3)
	v_mov_b32_e32 v44, v13
	v_mov_b32_e32 v45, v14
	v_mov_b32_e32 v56, v12
	v_mov_b32_e32 v57, v15
	s_waitcnt vmcnt(2)
	v_mov_b32_e32 v58, v9
	v_mov_b32_e32 v59, v10
	v_mov_b32_e32 v60, v8
	v_mov_b32_e32 v61, v11
	v_pk_add_f32 v[44:45], v[44:45], v[56:57]
	v_pk_add_f32 v[56:57], v[58:59], v[60:61]
	v_add_f32_e32 v55, v44, v45
	v_pk_add_f32 v[44:45], v[56:57], v[56:57] op_sel:[0,1] op_sel_hi:[1,0]
	s_waitcnt vmcnt(1)
	v_add_f32_e32 v62, v4, v5
	v_add_f32_e32 v64, v6, v7
	s_waitcnt vmcnt(0)
	v_mov_b32_e32 v67, v0
	v_mov_b32_e32 v63, v2
	v_mov_b32_e32 v65, v3
	v_add_f32_e32 v66, 0, v55
	v_mov_b32_e32 v45, v1
	v_pk_add_f32 v[58:59], v[62:63], v[64:65]
	v_pk_add_f32 v[44:45], v[66:67], v[44:45]
	s_nop 0
	v_pk_add_f32 v[44:45], v[44:45], v[58:59]
	s_nop 0
	v_add_f32_e32 v44, v44, v45
	s_nop 1
	v_add_f32_dpp v44, v44, v44 quad_perm:[1,0,3,2] row_mask:0xf bank_mask:0xf
	s_nop 1
	v_add_f32_dpp v44, v44, v44 quad_perm:[2,3,0,1] row_mask:0xf bank_mask:0xf
	s_nop 1
	v_add_f32_dpp v44, v44, v44 row_half_mirror row_mask:0xf bank_mask:0xf
	s_nop 1
	v_add_f32_dpp v44, v44, v44 row_mirror row_mask:0xf bank_mask:0xf
	v_mov_b32_e32 v45, v44
	s_nop 1
	v_permlane16_swap_b32 v44, v45
	v_add_f32_e32 v44, v44, v45
	v_mov_b32_e32 v45, v44
	s_nop 1
	v_permlane32_swap_b32 v44, v45
	v_add_f32_e32 v55, v44, v45
	v_fmamk_f32 v45, v55, 0xba800000, v15
	v_fmamk_f32 v44, v55, 0xba800000, v14
	v_fmamk_f32 v13, v55, 0xba800000, v13
	v_fmac_f32_e32 v12, 0xba800000, v55
	v_fmamk_f32 v11, v55, 0xba800000, v11
	v_fmamk_f32 v10, v55, 0xba800000, v10
	v_fmamk_f32 v9, v55, 0xba800000, v9
	v_fmac_f32_e32 v8, 0xba800000, v55
	v_pk_mul_f32 v[14:15], v[44:45], v[44:45]
	v_pk_mul_f32 v[56:57], v[12:13], v[12:13]
	v_pk_mul_f32 v[58:59], v[10:11], v[10:11]
	v_pk_mul_f32 v[60:61], v[8:9], v[8:9]
	v_fmamk_f32 v6, v55, 0xba800000, v6
	v_fmac_f32_e32 v4, 0xba800000, v55
	v_pk_mov_b32 v[66:67], v[56:57], v[14:15] op_sel:[1,0]
	v_mov_b32_e32 v57, v15
	v_pk_mov_b32 v[14:15], v[60:61], v[58:59] op_sel:[1,0]
	v_mov_b32_e32 v61, v59
	v_fmamk_f32 v7, v55, 0xba800000, v7
	v_fmamk_f32 v5, v55, 0xba800000, v5
	v_mul_f32_e32 v62, v4, v4
	v_mul_f32_e32 v64, v6, v6
	v_pk_add_f32 v[56:57], v[66:67], v[56:57]
	v_pk_add_f32 v[14:15], v[14:15], v[60:61]
	v_fmamk_f32 v3, v55, 0xba800000, v3
	v_fmamk_f32 v2, v55, 0xba800000, v2
	v_fmamk_f32 v1, v55, 0xba800000, v1
	v_fmac_f32_e32 v0, 0xba800000, v55
	v_pk_fma_f32 v[58:59], v[4:5], v[4:5], v[62:63] op_sel_hi:[1,1,0]
	v_pk_fma_f32 v[62:63], v[6:7], v[6:7], v[64:65] op_sel_hi:[1,1,0]
	v_pk_add_f32 v[56:57], v[56:57], v[56:57] op_sel_hi:[0,1]
	v_pk_add_f32 v[14:15], v[14:15], v[14:15] op_sel_hi:[0,1]
	v_mul_f32_e32 v58, v0, v0
	v_mul_f32_e32 v62, v1, v1
	v_mul_f32_e32 v56, v2, v2
	v_mul_f32_e32 v14, v3, v3
	v_pk_add_f32 v[58:59], v[58:59], v[62:63]
	v_pk_add_f32 v[14:15], v[56:57], v[14:15]
	s_nop 0
	v_pk_add_f32 v[14:15], v[58:59], v[14:15]
	s_nop 0
	v_add_f32_e32 v14, v14, v15
	s_nop 1
	v_add_f32_dpp v14, v14, v14 quad_perm:[1,0,3,2] row_mask:0xf bank_mask:0xf
	s_nop 1
	v_add_f32_dpp v14, v14, v14 quad_perm:[2,3,0,1] row_mask:0xf bank_mask:0xf
	s_nop 1
	v_add_f32_dpp v14, v14, v14 row_half_mirror row_mask:0xf bank_mask:0xf
	s_nop 1
	v_add_f32_dpp v14, v14, v14 row_mirror row_mask:0xf bank_mask:0xf
	v_mov_b32_e32 v15, v14
	s_nop 1
	v_permlane16_swap_b32 v14, v15
	v_add_f32_e32 v14, v14, v15
	v_mov_b32_e32 v15, v14
	s_nop 1
	v_permlane32_swap_b32 v14, v15
	v_add_f32_e32 v14, v14, v15
	v_fmamk_f32 v14, v14, 0x3a800000, v52
	v_mul_f32_e32 v15, 0x4b800000, v14
	v_cmp_gt_f32_e32 vcc, s22, v14
	s_nop 1
	v_cndmask_b32_e32 v14, v14, v15, vcc
	v_rsq_f32_e32 v14, v14
	s_nop 0
	v_mul_f32_e32 v15, 0x45800000, v14
	v_cndmask_b32_e32 v14, v14, v15, vcc
	s_and_saveexec_b64 s[4:5], s[8:9]
	s_cbranch_execz .LBB0_3109
	v_lshl_add_u64 v[58:59], s[90:91], 0, v[32:33]
	v_add_co_u32_e32 v58, vcc, 0x1fe00000, v58
	v_mul_f32_e32 v56, 0x3a800000, v55
	s_nop 0
	v_addc_co_u32_e32 v59, vcc, 0, v59, vcc
	v_mov_b32_e32 v57, v14
	global_store_dwordx2 v[58:59], v[56:57], off
	s_branch .LBB0_3109

.LBB0_3596:
	v_mul_hi_i32 v0, v53, s20
	v_lshrrev_b32_e32 v1, 31, v0
	v_ashrrev_i32_e32 v0, 11, v0
	v_add_u32_e32 v54, v0, v1
	v_mad_i32_i24 v1, v54, s21, v53
	v_cmp_gt_i32_e64 s[8:9], s2, v1
	v_cmp_lt_i32_e32 vcc, s22, v1
	s_and_saveexec_b64 s[4:5], vcc
	s_xor_b64 s[4:5], exec, s[4:5]
	v_mul_i32_i24_e32 v0, 0xffffdf00, v54
	v_lshl_add_u32 v0, v54, 13, v0
	v_add3_u32 v0, v53, v0, s23
	s_or_saveexec_b64 s[4:5], s[4:5]
	v_mov_b64_e32 v[2:3], s[88:89]
	s_xor_b64 exec, exec, s[4:5]
	v_lshl_add_u32 v0, v54, 8, v1
	v_mov_b64_e32 v[2:3], s[70:71]
	s_or_b64 exec, exec, s[4:5]
	v_ashrrev_i32_e32 v1, 31, v0
	v_lshlrev_b64 v[0:1], 12, v[0:1]
	v_lshl_add_u64 v[0:1], v[2:3], 0, v[0:1]
	v_lshl_add_u64 v[0:1], v[0:1], 0, v[36:37]
	global_load_dwordx4 v[12:15], v[0:1], off nt
	global_load_dwordx4 v[8:11], v[0:1], off offset:1024 nt
	global_load_dwordx4 v[4:7], v[0:1], off offset:2048 nt
	s_nop 0
	global_load_dwordx4 v[0:3], v[0:1], off offset:3072 nt
	s_waitcnt vmcnt(3)
	v_mov_b32_e32 v44, v13
	v_mov_b32_e32 v45, v14
	v_mov_b32_e32 v56, v12
	v_mov_b32_e32 v57, v15
	s_waitcnt vmcnt(2)
	v_mov_b32_e32 v58, v9
	v_mov_b32_e32 v59, v10
	v_mov_b32_e32 v60, v8
	v_mov_b32_e32 v61, v11
	v_pk_add_f32 v[44:45], v[44:45], v[56:57]
	v_pk_add_f32 v[56:57], v[58:59], v[60:61]
	v_add_f32_e32 v55, v44, v45
	v_pk_add_f32 v[44:45], v[56:57], v[56:57] op_sel:[0,1] op_sel_hi:[1,0]
	s_waitcnt vmcnt(1)
	v_add_f32_e32 v62, v4, v5
	v_add_f32_e32 v64, v6, v7
	s_waitcnt vmcnt(0)
	v_mov_b32_e32 v67, v0
	v_mov_b32_e32 v63, v2
	v_mov_b32_e32 v65, v3
	v_add_f32_e32 v66, 0, v55
	v_mov_b32_e32 v45, v1
	v_pk_add_f32 v[58:59], v[62:63], v[64:65]
	v_pk_add_f32 v[44:45], v[66:67], v[44:45]
	s_nop 0
	v_pk_add_f32 v[44:45], v[44:45], v[58:59]
	s_nop 0
	v_add_f32_e32 v44, v44, v45
	s_nop 1
	v_add_f32_dpp v44, v44, v44 quad_perm:[1,0,3,2] row_mask:0xf bank_mask:0xf
	s_nop 1
	v_add_f32_dpp v44, v44, v44 quad_perm:[2,3,0,1] row_mask:0xf bank_mask:0xf
	s_nop 1
	v_add_f32_dpp v44, v44, v44 row_half_mirror row_mask:0xf bank_mask:0xf
	s_nop 1
	v_add_f32_dpp v44, v44, v44 row_mirror row_mask:0xf bank_mask:0xf
	v_mov_b32_e32 v45, v44
	s_nop 1
	v_permlane16_swap_b32 v44, v45
	v_add_f32_e32 v44, v44, v45
	v_mov_b32_e32 v45, v44
	s_nop 1
	v_permlane32_swap_b32 v44, v45
	v_add_f32_e32 v55, v44, v45
	v_fmamk_f32 v45, v55, 0xba800000, v15
	v_fmamk_f32 v44, v55, 0xba800000, v14
	v_fmamk_f32 v13, v55, 0xba800000, v13
	v_fmac_f32_e32 v12, 0xba800000, v55
	v_fmamk_f32 v11, v55, 0xba800000, v11
	v_fmamk_f32 v10, v55, 0xba800000, v10
	v_fmamk_f32 v9, v55, 0xba800000, v9
	v_fmac_f32_e32 v8, 0xba800000, v55
	v_pk_mul_f32 v[14:15], v[44:45], v[44:45]
	v_pk_mul_f32 v[56:57], v[12:13], v[12:13]
	v_pk_mul_f32 v[58:59], v[10:11], v[10:11]
	v_pk_mul_f32 v[60:61], v[8:9], v[8:9]
	v_fmamk_f32 v6, v55, 0xba800000, v6
	v_fmac_f32_e32 v4, 0xba800000, v55
	v_pk_mov_b32 v[66:67], v[56:57], v[14:15] op_sel:[1,0]
	v_mov_b32_e32 v57, v15
	v_pk_mov_b32 v[14:15], v[60:61], v[58:59] op_sel:[1,0]
	v_mov_b32_e32 v61, v59
	v_fmamk_f32 v7, v55, 0xba800000, v7
	v_fmamk_f32 v5, v55, 0xba800000, v5
	v_mul_f32_e32 v62, v4, v4
	v_mul_f32_e32 v64, v6, v6
	v_pk_add_f32 v[56:57], v[66:67], v[56:57]
	v_pk_add_f32 v[14:15], v[14:15], v[60:61]
	v_fmamk_f32 v3, v55, 0xba800000, v3
	v_fmamk_f32 v2, v55, 0xba800000, v2
	v_fmamk_f32 v1, v55, 0xba800000, v1
	v_fmac_f32_e32 v0, 0xba800000, v55
	v_pk_fma_f32 v[58:59], v[4:5], v[4:5], v[62:63] op_sel_hi:[1,1,0]
	v_pk_fma_f32 v[62:63], v[6:7], v[6:7], v[64:65] op_sel_hi:[1,1,0]
	v_pk_add_f32 v[56:57], v[56:57], v[56:57] op_sel_hi:[0,1]
	v_pk_add_f32 v[14:15], v[14:15], v[14:15] op_sel_hi:[0,1]
	v_mul_f32_e32 v58, v0, v0
	v_mul_f32_e32 v62, v1, v1
	v_mul_f32_e32 v56, v2, v2
	v_mul_f32_e32 v14, v3, v3
	v_pk_add_f32 v[58:59], v[58:59], v[62:63]
	v_pk_add_f32 v[14:15], v[56:57], v[14:15]
	s_nop 0
	v_pk_add_f32 v[14:15], v[58:59], v[14:15]
	s_nop 0
	v_add_f32_e32 v14, v14, v15
	s_nop 1
	v_add_f32_dpp v14, v14, v14 quad_perm:[1,0,3,2] row_mask:0xf bank_mask:0xf
	s_nop 1
	v_add_f32_dpp v14, v14, v14 quad_perm:[2,3,0,1] row_mask:0xf bank_mask:0xf
	s_nop 1
	v_add_f32_dpp v14, v14, v14 row_half_mirror row_mask:0xf bank_mask:0xf
	s_nop 1
	v_add_f32_dpp v14, v14, v14 row_mirror row_mask:0xf bank_mask:0xf
	v_mov_b32_e32 v15, v14
	s_nop 1
	v_permlane16_swap_b32 v14, v15
	v_add_f32_e32 v14, v14, v15
	v_mov_b32_e32 v15, v14
	s_nop 1
	v_permlane32_swap_b32 v14, v15
	v_add_f32_e32 v14, v14, v15
	v_fmamk_f32 v14, v14, 0x3a800000, v52
	v_mul_f32_e32 v15, 0x4b800000, v14
	v_cmp_gt_f32_e32 vcc, s24, v14
	s_nop 1
	v_cndmask_b32_e32 v14, v14, v15, vcc
	v_rsq_f32_e32 v14, v14
	s_nop 0
	v_mul_f32_e32 v15, 0x45800000, v14
	v_cndmask_b32_e32 v14, v14, v15, vcc
	s_and_saveexec_b64 s[4:5], s[6:7]
	s_cbranch_execz .LBB0_3595
	v_lshl_add_u64 v[58:59], s[90:91], 0, v[32:33]
	v_add_co_u32_e32 v58, vcc, 0x1fe00000, v58
	v_mul_f32_e32 v56, 0x3a800000, v55
	s_nop 0
	v_addc_co_u32_e32 v59, vcc, 0, v59, vcc
	v_mov_b32_e32 v57, v14
	global_store_dwordx2 v[58:59], v[56:57], off
	s_branch .LBB0_3595

.LBB0_3804:
	s_or_b64 exec, exec, s[4:5]
	v_ashrrev_i32_e32 v1, 31, v0
	v_lshlrev_b64 v[0:1], 12, v[0:1]
	v_lshl_add_u64 v[0:1], v[2:3], 0, v[0:1]
	v_lshl_add_u64 v[20:21], v[0:1], 0, v[152:153]
	global_load_dwordx4 v[30:33], v[20:21], off nt
	global_load_dwordx4 v[34:37], v[20:21], off offset:1024 nt
	global_load_dwordx4 v[38:41], v[20:21], off offset:2048 nt
	global_load_dwordx4 v[0:3], v[20:21], off offset:3072 nt
	v_add_u32_e32 v150, s52, v150
	s_waitcnt vmcnt(3)
	v_mov_b32_e32 v42, v31
	v_mov_b32_e32 v43, v32
	v_mov_b32_e32 v44, v30
	v_mov_b32_e32 v45, v33
	s_waitcnt vmcnt(2)
	v_mov_b32_e32 v46, v35
	v_mov_b32_e32 v47, v36
	v_mov_b32_e32 v48, v34
	v_mov_b32_e32 v49, v37
	v_pk_add_f32 v[42:43], v[42:43], v[44:45]
	v_pk_add_f32 v[44:45], v[46:47], v[48:49]
	v_add_f32_e32 v29, v42, v43
	v_pk_add_f32 v[42:43], v[44:45], v[44:45] op_sel:[0,1] op_sel_hi:[1,0]
	s_waitcnt vmcnt(1)
	v_add_f32_e32 v50, v38, v39
	v_add_f32_e32 v52, v40, v41
	s_waitcnt vmcnt(0)
	v_mov_b32_e32 v55, v0
	v_mov_b32_e32 v51, v2
	v_mov_b32_e32 v53, v3
	v_add_f32_e32 v54, 0, v29
	v_mov_b32_e32 v43, v1
	v_pk_add_f32 v[46:47], v[50:51], v[52:53]
	v_pk_add_f32 v[42:43], v[54:55], v[42:43]
	s_nop 0
	v_pk_add_f32 v[42:43], v[42:43], v[46:47]
	s_nop 0
	v_add_f32_e32 v29, v42, v43
	s_nop 1
	v_add_f32_dpp v29, v29, v29 quad_perm:[1,0,3,2] row_mask:0xf bank_mask:0xf
	s_nop 1
	v_add_f32_dpp v29, v29, v29 quad_perm:[2,3,0,1] row_mask:0xf bank_mask:0xf
	s_nop 1
	v_add_f32_dpp v29, v29, v29 row_half_mirror row_mask:0xf bank_mask:0xf
	s_nop 1
	v_add_f32_dpp v29, v29, v29 row_mirror row_mask:0xf bank_mask:0xf
	v_mov_b32_e32 v42, v29
	s_nop 1
	v_permlane16_swap_b32 v29, v42
	v_add_f32_e32 v29, v29, v42
	global_load_dwordx4 v[42:45], v[4:5], off
	global_load_dwordx4 v[46:49], v[6:7], off
	ds_bpermute_b32 v50, v27, v29
	s_waitcnt lgkmcnt(0)
	v_add_f32_e32 v29, v29, v50
	v_fmamk_f32 v31, v29, 0xba800000, v31
	v_fmamk_f32 v30, v29, 0xba800000, v30
	v_fmamk_f32 v33, v29, 0xba800000, v33
	v_fmac_f32_e32 v32, 0xba800000, v29
	v_fmamk_f32 v35, v29, 0xba800000, v35
	v_fmamk_f32 v34, v29, 0xba800000, v34
	v_fmamk_f32 v37, v29, 0xba800000, v37
	v_fmac_f32_e32 v36, 0xba800000, v29
	v_pk_mul_f32 v[50:51], v[32:33], v[32:33]
	v_pk_mul_f32 v[52:53], v[30:31], v[30:31]
	v_pk_mul_f32 v[54:55], v[36:37], v[36:37]
	v_pk_mul_f32 v[56:57], v[34:35], v[34:35]
	v_fmamk_f32 v38, v29, 0xba800000, v38
	v_fmac_f32_e32 v40, 0xba800000, v29
	v_pk_mov_b32 v[62:63], v[52:53], v[50:51] op_sel:[1,0]
	v_mov_b32_e32 v53, v51
	v_pk_mov_b32 v[50:51], v[56:57], v[54:55] op_sel:[1,0]
	v_mov_b32_e32 v57, v55
	v_fmamk_f32 v39, v29, 0xba800000, v39
	v_fmamk_f32 v41, v29, 0xba800000, v41
	v_mul_f32_e32 v58, v38, v38
	v_mul_f32_e32 v60, v40, v40
	v_pk_add_f32 v[52:53], v[62:63], v[52:53]
	v_pk_add_f32 v[50:51], v[50:51], v[56:57]
	v_fmamk_f32 v3, v29, 0xba800000, v3
	v_fmamk_f32 v2, v29, 0xba800000, v2
	v_fmamk_f32 v1, v29, 0xba800000, v1
	v_fmac_f32_e32 v0, 0xba800000, v29
	v_pk_fma_f32 v[54:55], v[38:39], v[38:39], v[58:59] op_sel_hi:[1,1,0]
	v_pk_fma_f32 v[58:59], v[40:41], v[40:41], v[60:61] op_sel_hi:[1,1,0]
	v_pk_add_f32 v[52:53], v[52:53], v[52:53] op_sel_hi:[0,1]
	v_pk_add_f32 v[50:51], v[50:51], v[50:51] op_sel_hi:[0,1]
	v_mul_f32_e32 v54, v0, v0
	v_mul_f32_e32 v58, v1, v1
	v_mul_f32_e32 v52, v2, v2
	v_mul_f32_e32 v50, v3, v3
	v_pk_add_f32 v[54:55], v[54:55], v[58:59]
	v_pk_add_f32 v[50:51], v[52:53], v[50:51]
	s_nop 0
	v_pk_add_f32 v[50:51], v[54:55], v[50:51]
	s_nop 0
	v_add_f32_e32 v29, v50, v51
	s_nop 1
	v_add_f32_dpp v29, v29, v29 quad_perm:[1,0,3,2] row_mask:0xf bank_mask:0xf
	s_nop 1
	v_add_f32_dpp v29, v29, v29 quad_perm:[2,3,0,1] row_mask:0xf bank_mask:0xf
	s_nop 1
	v_add_f32_dpp v29, v29, v29 row_half_mirror row_mask:0xf bank_mask:0xf
	s_nop 1
	v_add_f32_dpp v29, v29, v29 row_mirror row_mask:0xf bank_mask:0xf
	v_mov_b32_e32 v50, v29
	s_nop 1
	v_permlane16_swap_b32 v29, v50
	v_add_f32_e32 v29, v29, v50
	v_mov_b32_e32 v50, v29
	s_nop 1
	v_permlane32_swap_b32 v29, v50
	v_add_f32_e32 v29, v29, v50
	v_fmamk_f32 v29, v29, 0x3a800000, v28
	v_mul_f32_e32 v50, 0x4b800000, v29
	v_cmp_gt_f32_e32 vcc, s10, v29
	s_nop 1
	v_cndmask_b32_e32 v29, v29, v50, vcc
	v_rsq_f32_e32 v29, v29
	s_nop 0
	v_mul_f32_e32 v50, 0x45800000, v29
	v_cndmask_b32_e32 v50, v29, v50, vcc
	v_pk_mul_f32 v[30:31], v[30:31], v[50:51] op_sel_hi:[1,0]
	v_pk_mul_f32 v[32:33], v[32:33], v[50:51] op_sel_hi:[1,0]
	s_waitcnt vmcnt(0)
	v_pk_fma_f32 v[30:31], v[42:43], v[30:31], v[46:47]
	v_pk_fma_f32 v[32:33], v[44:45], v[32:33], v[48:49]
	global_store_dwordx4 v[20:21], v[30:33], off
	global_load_dwordx4 v[30:33], v[8:9], off
	s_nop 0
	global_load_dwordx4 v[42:45], v[10:11], off
	v_pk_mul_f32 v[36:37], v[36:37], v[50:51] op_sel_hi:[1,0]
	v_pk_mul_f32 v[34:35], v[34:35], v[50:51] op_sel_hi:[1,0]
	v_pk_mul_f32 v[40:41], v[40:41], v[50:51] op_sel_hi:[1,0]
	v_pk_mul_f32 v[38:39], v[38:39], v[50:51] op_sel_hi:[1,0]
	v_cmp_lt_i32_e32 vcc, s11, v150
	v_pk_mul_f32 v[2:3], v[2:3], v[50:51] op_sel_hi:[1,0]
	v_pk_mul_f32 v[0:1], v[0:1], v[50:51] op_sel_hi:[1,0]
	s_or_b64 s[2:3], vcc, s[2:3]
	s_waitcnt vmcnt(0)
	v_pk_fma_f32 v[30:31], v[30:31], v[34:35], v[42:43]
	v_pk_fma_f32 v[32:33], v[32:33], v[36:37], v[44:45]
	global_store_dwordx4 v[20:21], v[30:33], off offset:1024
	global_load_dwordx4 v[30:33], v[12:13], off
	s_nop 0
	global_load_dwordx4 v[34:37], v[14:15], off
	s_waitcnt vmcnt(0)
	v_pk_fma_f32 v[30:31], v[30:31], v[38:39], v[34:35]
	v_pk_fma_f32 v[32:33], v[32:33], v[40:41], v[36:37]
	global_store_dwordx4 v[20:21], v[30:33], off offset:2048
	global_load_dwordx4 v[30:33], v[16:17], off
	s_nop 0
	global_load_dwordx4 v[34:37], v[18:19], off
	s_waitcnt vmcnt(0)
	v_pk_fma_f32 v[0:1], v[30:31], v[0:1], v[34:35]
	v_pk_fma_f32 v[2:3], v[32:33], v[2:3], v[36:37]
	global_store_dwordx4 v[20:21], v[0:3], off offset:3072
	s_andn2_b64 exec, exec, s[2:3]
	s_cbranch_execz .LBB0_3809
